# GEMM prologues: issue the second K-step's six LDS-DMA loads before the first wait/barrier (one exposed latency instead of two)
# speedup vs baseline: 1.0061x; 1.0061x over previous
; #define PG8_STAGE(bufoff, gbase, voff) do { _Pragma("unroll") for (int _i = 0; _i < 2; ++_i) \
;         __builtin_amdgcn_global_load_lds((const unsigned*)((const char*)(gbase) + (voff)[_i]), (LAS unsigned*)(lds + (bufoff) + ldsw + _i * 8192), 16, 0, 0); } while (0)
; #define PG8_WAIT_V(n) asm volatile("s_waitcnt vmcnt(" #n ")" ::: "memory")
; #define PG8_BAR __builtin_amdgcn_s_barrier()
; template <class Epi, bool HALFM = false>
; DI void gemm_phase(LAS unsigned char* lds, const Gemm g, const StaticOrder& S, const Epi& E) {
;     ...
;     f32x4 acc[2][2][4][2];
; #pragma unroll
;     for (int a = 0; a < 2; ++a)
; #pragma unroll
;         for (int b = 0; b < 2; ++b)
; #pragma unroll
;             for (int m = 0; m < 4; ++m)
; #pragma unroll
;                 for (int n = 0; n < 2; ++n) acc[a][b][m][n] = (f32x4){0.f, 0.f, 0.f, 0.f};
;     bf16x8 At[4][2], B0[2][2], B1[2][2];
;     const char* cA = (const char*)g.A + (size_t)cur.pm * tstepA; const char* cB = (const char*)g.Bt + (size_t)cur.pn * tstepB;
;     PG8_STAGE(PG8_SB(0, 0), cB, voffB); PG8_STAGE(PG8_SB(0, 1), cB + hstepB, voffB); PG8_STAGE(PG8_SA(0, 0), cA, voffA); PG8_STAGE(PG8_SA(0, 1), cA + hstepA, voffA);
;     if (wr == 1) PG8_BAR;
;     PG8_WAIT_V(2); PG8_BAR;
;     PG8_STAGE(PG8_SB(1, 0), cB + kstep, voffB); PG8_STAGE(PG8_SA(1, 0), cA + kstep, voffA); PG8_STAGE(PG8_SB(1, 1), cB + hstepB + kstep, voffB);
;     PG8_WAIT_V(6); PG8_BAR;
.LBB0_240:
	v_readlane_b32 s14, v254, 8
	v_readlane_b32 s15, v254, 9
	s_waitcnt lgkmcnt(0)
	s_add_u32 s37, s8, s14
	s_addc_u32 s38, s9, s15
	s_lshl_b32 s1, s1, 5
	s_and_b32 s40, s1, 0x60
	s_lshl_b32 s39, s4, 6
	s_lshl_b32 s8, s4, 13
	s_lshl_b32 s1, s40, 7
	v_readlane_b32 s14, v254, 61
	v_readlane_b32 s15, v254, 62
	s_add_u32 s41, s14, 0xcb4c800
	s_addc_u32 s42, s15, 0
	v_readlane_b32 s4, v254, 10
	v_readlane_b32 s5, v254, 11
	s_add_u32 s4, s14, s4
	s_addc_u32 s5, s15, s5
	s_add_u32 s14, s4, 0x1b409200
	s_addc_u32 s15, s5, 0
	s_add_i32 m0, s31, 0x18000
	v_lshl_add_u64 v[8:9], v[8:9], 0, s[2:3]
	global_load_lds_dwordx4 v[8:9], off
	v_lshl_add_u64 v[6:7], v[6:7], 0, s[2:3]
	s_add_i32 m0, s31, 0x1a000
	s_add_i32 s43, s31, 0x8000
	s_add_i32 s44, s31, 0xa000
	global_load_lds_dwordx4 v[6:7], off
	v_lshl_add_u64 v[2:3], v[2:3], 0, s[2:3]
	s_mov_b32 m0, s43
	s_add_u32 s4, s12, 0x20080
	global_load_lds_dwordx4 v[2:3], off
	v_lshl_add_u64 v[2:3], v[4:5], 0, s[2:3]
	s_mov_b32 m0, s44
	s_addc_u32 s5, s13, 0
	global_load_lds_dwordx4 v[2:3], off
	s_add_i32 m0, s31, 0x1c000
	v_lshl_add_u64 v[2:3], s[4:5], 0, v[0:1]
	global_load_lds_dwordx4 v[2:3], off
	v_lshl_add_u64 v[2:3], s[4:5], 0, v[178:179]
	s_add_i32 m0, s31, 0x1e000
	s_movk_i32 s4, 0x3c0
	global_load_lds_dwordx4 v[2:3], off
	s_waitcnt vmcnt(8)
	s_barrier
	v_and_b32_e32 v2, 48, v10
	v_lshlrev_b32_e32 v3, 6, v10
	v_and_or_b32 v2, v3, s4, v2
	v_lshlrev_b32_e32 v3, 2, v10
	v_and_b32_e32 v3, 32, v3
	v_bitop3_b32 v6, v2, s8, v3 bitop3:0xde
	v_bitop3_b32 v205, s1, v2, v3 bitop3:0xf6
	v_lshlrev_b32_e32 v2, 13, v15
	v_and_b32_e32 v2, 0xffffc000, v2
	v_lshl_add_u32 v2, v14, 10, v2
	v_and_b32_e32 v3, 1, v15
	v_lshl_or_b32 v2, v3, 6, v2
	v_lshl_add_u32 v184, v16, 1, v2
	v_lshlrev_b32_e32 v2, 13, v11
	v_and_b32_e32 v2, 0xffffc000, v2
	v_lshl_add_u32 v2, v12, 10, v2
	v_and_b32_e32 v3, 1, v11
	s_waitcnt vmcnt(6)
	v_lshl_or_b32 v2, v3, 6, v2
	v_mov_b32_e32 v4, v1
	v_mov_b32_e32 v5, v1
	s_cmpk_lt_u32 s0, 0x100
	v_lshl_add_u32 v186, v13, 1, v2
	v_mov_b32_e32 v2, v1
	v_mov_b32_e32 v3, v1
	v_add_u32_e32 v210, 0x100, v6
	v_mov_b64_e32 v[8:9], v[4:5]
	v_mov_b64_e32 v[20:21], v[4:5]
	v_mov_b64_e32 v[24:25], v[4:5]
	v_mov_b64_e32 v[44:45], v[4:5]
	v_mov_b64_e32 v[48:49], v[4:5]
	v_mov_b64_e32 v[76:77], v[4:5]
	v_mov_b64_e32 v[80:81], v[4:5]
	v_mov_b64_e32 v[12:13], v[4:5]
	v_mov_b64_e32 v[16:17], v[4:5]
	v_mov_b64_e32 v[36:37], v[4:5]
	v_mov_b64_e32 v[40:41], v[4:5]
	v_mov_b64_e32 v[68:69], v[4:5]
	v_mov_b64_e32 v[72:73], v[4:5]
	v_mov_b64_e32 v[104:105], v[4:5]
	v_mov_b64_e32 v[108:109], v[4:5]
	v_readlane_b32 s4, v253, 37
	s_cselect_b64 s[16:17], -1, 0
	v_mov_b32_e32 v185, v1
	v_mov_b32_e32 v187, v1
	s_mov_b32 s45, 0
	v_mov_b64_e32 v[6:7], v[2:3]
	v_mov_b64_e32 v[18:19], v[2:3]
	v_mov_b64_e32 v[22:23], v[2:3]
	v_mov_b64_e32 v[42:43], v[2:3]
	v_mov_b64_e32 v[46:47], v[2:3]
	v_mov_b64_e32 v[74:75], v[2:3]
	v_mov_b64_e32 v[78:79], v[2:3]
	v_mov_b64_e32 v[10:11], v[2:3]
	v_mov_b64_e32 v[14:15], v[2:3]
	v_mov_b64_e32 v[34:35], v[2:3]
	v_mov_b64_e32 v[38:39], v[2:3]
	v_mov_b64_e32 v[66:67], v[2:3]
	v_mov_b64_e32 v[70:71], v[2:3]
	v_mov_b64_e32 v[102:103], v[2:3]
	v_mov_b64_e32 v[106:107], v[2:3]
	v_readlane_b32 s0, v253, 24
	s_mov_b32 s1, s4
	s_barrier
	v_readlane_b32 s5, v253, 38
	s_branch .LBB0_243

; #define PG8_STAGE(bufoff, gbase, voff) do { _Pragma("unroll") for (int _i = 0; _i < 2; ++_i) \
;         __builtin_amdgcn_global_load_lds((const unsigned*)((const char*)(gbase) + (voff)[_i]), (LAS unsigned*)(lds + (bufoff) + ldsw + _i * 8192), 16, 0, 0); } while (0)
; #define PG8_WAIT_V(n) asm volatile("s_waitcnt vmcnt(" #n ")" ::: "memory")
; #define PG8_BAR __builtin_amdgcn_s_barrier()
; template <class Epi, bool HALFM = false>
; DI void gemm_phase(LAS unsigned char* lds, const Gemm g, const StaticOrder& S, const Epi& E) {
;     ...
;     const char* cA = (const char*)g.A + (size_t)cur.pm * tstepA; const char* cB = (const char*)g.Bt + (size_t)cur.pn * tstepB;
;     PG8_STAGE(PG8_SB(0, 0), cB, voffB); PG8_STAGE(PG8_SB(0, 1), cB + hstepB, voffB); PG8_STAGE(PG8_SA(0, 0), cA, voffA); PG8_STAGE(PG8_SA(0, 1), cA + hstepA, voffA);
;     if (wr == 1) PG8_BAR;
;     PG8_WAIT_V(2); PG8_BAR;
;     PG8_STAGE(PG8_SB(1, 0), cB + kstep, voffB); PG8_STAGE(PG8_SA(1, 0), cA + kstep, voffA); PG8_STAGE(PG8_SB(1, 1), cB + hstepB + kstep, voffB);
;     PG8_WAIT_V(6); PG8_BAR;
.LBB0_278:
	v_readlane_b32 s8, v254, 14
	v_readlane_b32 s9, v254, 15
	s_and_b64 s[8:9], s[8:9], exec
	s_waitcnt lgkmcnt(0)
	s_cselect_b32 s19, s7, s15
	s_cselect_b32 s18, s6, s14
	s_lshl_b32 s1, s1, 5
	s_and_b32 s40, s1, 0x60
	s_lshl_b32 s39, s4, 6
	s_lshl_b32 s4, s4, 13
	s_lshl_b32 s1, s40, 7
	v_readlane_b32 s6, v254, 18
	v_readlane_b32 s5, v254, 49
	v_readlane_b32 s7, v254, 19
	s_add_u32 s20, s5, s6
	v_readlane_b32 s5, v254, 50
	s_addc_u32 s21, s5, s7
	s_add_i32 m0, s35, 0x18000
	v_lshl_add_u64 v[10:11], v[10:11], 0, s[2:3]
	global_load_lds_dwordx4 v[10:11], off
	v_lshl_add_u64 v[6:7], v[6:7], 0, s[2:3]
	s_add_i32 m0, s35, 0x1a000
	s_add_i32 s41, s35, 0x8000
	global_load_lds_dwordx4 v[6:7], off
	v_lshl_add_u64 v[6:7], v[8:9], 0, s[2:3]
	s_mov_b32 m0, s41
	s_add_i32 s42, s35, 0xa000
	global_load_lds_dwordx4 v[6:7], off
	v_lshl_add_u64 v[6:7], v[12:13], 0, s[2:3]
	s_mov_b32 m0, s42
	v_lshl_add_u64 v[4:5], v[4:5], 0, s[2:3]
	global_load_lds_dwordx4 v[6:7], off
	s_add_i32 m0, s35, 0x1c000
	v_lshl_add_u64 v[2:3], v[2:3], 0, s[2:3]
	global_load_lds_dwordx4 v[4:5], off
	s_add_i32 m0, s35, 0x1e000
	s_movk_i32 s5, 0x3c0
	global_load_lds_dwordx4 v[2:3], off
	s_waitcnt vmcnt(8)
	s_barrier
	v_and_b32_e32 v2, 48, v14
	v_lshlrev_b32_e32 v3, 6, v14
	v_and_or_b32 v2, v3, s5, v2
	v_lshlrev_b32_e32 v3, 2, v14
	v_and_b32_e32 v3, 32, v3
	v_bitop3_b32 v4, v2, s4, v3 bitop3:0xde
	v_bitop3_b32 v244, s1, v2, v3 bitop3:0xf6
	v_add_u32_e32 v2, v20, v18
	v_add_lshl_u32 v2, v2, v19, 1
	v_mov_b32_e32 v3, v1
	s_waitcnt vmcnt(6)
	v_lshl_add_u64 v[214:215], s[24:25], 0, v[2:3]
	v_add_u32_e32 v2, v17, v15
	s_cmpk_lt_u32 s0, 0x100
	v_add_lshl_u32 v2, v2, v16, 1
	s_cselect_b64 s[22:23], -1, 0
	v_lshl_add_u64 v[216:217], s[24:25], 0, v[2:3]
	s_mov_b32 s43, 0
	v_add_u32_e32 v245, 0x100, v4
	v_readlane_b32 s0, v253, 26
	v_readlane_b32 s1, v253, 25
	s_barrier
	s_branch .LBB0_281

; #define PG8_STAGE(bufoff, gbase, voff) do { _Pragma("unroll") for (int _i = 0; _i < 2; ++_i) \
;         __builtin_amdgcn_global_load_lds((const unsigned*)((const char*)(gbase) + (voff)[_i]), (LAS unsigned*)(lds + (bufoff) + ldsw + _i * 8192), 16, 0, 0); } while (0)
; #define PG8_WAIT_V(n) asm volatile("s_waitcnt vmcnt(" #n ")" ::: "memory")
; #define PG8_BAR __builtin_amdgcn_s_barrier()
; template <class Epi, bool HALFM = false>
; DI void gemm_phase(LAS unsigned char* lds, const Gemm g, const StaticOrder& S, const Epi& E) {
;     ...
;     const char* cA = (const char*)g.A + (size_t)cur.pm * tstepA; const char* cB = (const char*)g.Bt + (size_t)cur.pn * tstepB;
;     PG8_STAGE(PG8_SB(0, 0), cB, voffB); PG8_STAGE(PG8_SB(0, 1), cB + hstepB, voffB); PG8_STAGE(PG8_SA(0, 0), cA, voffA); PG8_STAGE(PG8_SA(0, 1), cA + hstepA, voffA);
;     if (wr == 1) PG8_BAR;
;     PG8_WAIT_V(2); PG8_BAR;
;     PG8_STAGE(PG8_SB(1, 0), cB + kstep, voffB); PG8_STAGE(PG8_SA(1, 0), cA + kstep, voffA); PG8_STAGE(PG8_SB(1, 1), cB + hstepB + kstep, voffB);
;     PG8_WAIT_V(6); PG8_BAR;
.LBB0_355:
	s_lshl_b32 s1, s1, 5
	s_and_b32 s50, s1, 0x60
	s_lshl_b32 s49, s4, 6
	s_lshl_b32 s8, s4, 13
	s_lshl_b32 s1, s50, 7
	s_cmp_eq_u64 s[6:7], 0
	s_cselect_b64 s[24:25], -1, 0
	s_cmp_lg_u64 s[6:7], 0
	s_cselect_b64 s[26:27], -1, 0
	s_cmp_eq_u64 s[22:23], 0
	s_cselect_b64 s[28:29], -1, 0
	s_add_i32 m0, s45, 0x18000
	v_lshl_add_u64 v[8:9], v[8:9], 0, s[2:3]
	global_load_lds_dwordx4 v[8:9], off
	v_lshl_add_u64 v[6:7], v[6:7], 0, s[2:3]
	s_add_i32 m0, s45, 0x1a000
	s_add_i32 s51, s45, 0x8000
	s_add_i32 s52, s45, 0xa000
	global_load_lds_dwordx4 v[6:7], off
	v_lshl_add_u64 v[2:3], v[2:3], 0, s[2:3]
	s_mov_b32 m0, s51
	s_add_u32 s4, s12, 0x18080
	global_load_lds_dwordx4 v[2:3], off
	v_lshl_add_u64 v[2:3], v[4:5], 0, s[2:3]
	s_mov_b32 m0, s52
	s_addc_u32 s5, s13, 0
	global_load_lds_dwordx4 v[2:3], off
	s_add_i32 m0, s45, 0x1c000
	v_lshl_add_u64 v[2:3], s[4:5], 0, v[0:1]
	global_load_lds_dwordx4 v[2:3], off
	v_lshl_add_u64 v[2:3], s[4:5], 0, v[130:131]
	s_add_i32 m0, s45, 0x1e000
	s_movk_i32 s4, 0x3c0
	global_load_lds_dwordx4 v[2:3], off
	s_waitcnt vmcnt(8)
	s_barrier
	v_and_b32_e32 v2, 48, v10
	v_lshlrev_b32_e32 v3, 6, v10
	v_and_or_b32 v2, v3, s4, v2
	v_lshlrev_b32_e32 v3, 2, v10
	v_and_b32_e32 v3, 32, v3
	s_movk_i32 s4, 0x2700
	v_bitop3_b32 v4, v2, s8, v3 bitop3:0xde
	v_bitop3_b32 v148, s1, v2, v3 bitop3:0xf6
	v_lshrrev_b32_e32 v3, 1, v16
	v_mul_lo_u32 v2, v15, s4
	s_mov_b32 s5, 0x27000
	s_cmpk_lt_u32 s0, 0x100
	v_mad_u64_u32 v[2:3], s[0:1], v3, s5, v[2:3]
	v_or_b32_e32 v2, v2, v17
	v_add_lshl_u32 v2, v2, v18, 1
	v_mov_b32_e32 v3, v1
	s_mov_b64 s[6:7], 0x270080
	v_lshl_add_u64 v[136:137], v[2:3], 0, s[6:7]
	v_lshrrev_b32_e32 v3, 1, v11
	v_mul_lo_u32 v2, v12, s4
	v_mad_u64_u32 v[2:3], s[0:1], v3, s5, v[2:3]
	s_waitcnt vmcnt(6)
	v_or_b32_e32 v2, v2, v13
	v_add_lshl_u32 v2, v2, v14, 1
	v_mov_b32_e32 v3, v1
	s_cselect_b64 s[30:31], -1, 0
	v_lshl_add_u64 v[138:139], v[2:3], 0, s[6:7]
	s_mov_b32 s53, 0
	v_add_u32_e32 v149, 0x100, v4
	v_readlane_b32 s0, v253, 28
	v_readlane_b32 s1, v253, 27
	s_barrier
	s_branch .LBB0_358

; #define PG8_STAGE(bufoff, gbase, voff) do { _Pragma("unroll") for (int _i = 0; _i < 2; ++_i) \
;         __builtin_amdgcn_global_load_lds((const unsigned*)((const char*)(gbase) + (voff)[_i]), (LAS unsigned*)(lds + (bufoff) + ldsw + _i * 8192), 16, 0, 0); } while (0)
; #define PG8_WAIT_V(n) asm volatile("s_waitcnt vmcnt(" #n ")" ::: "memory")
; #define PG8_BAR __builtin_amdgcn_s_barrier()
; template <class Epi, bool HALFM = false>
; DI void gemm_phase(LAS unsigned char* lds, const Gemm g, const StaticOrder& S, const Epi& E) {
;     ...
;     const char* cA = (const char*)g.A + (size_t)cur.pm * tstepA; const char* cB = (const char*)g.Bt + (size_t)cur.pn * tstepB;
;     PG8_STAGE(PG8_SB(0, 0), cB, voffB); PG8_STAGE(PG8_SB(0, 1), cB + hstepB, voffB); PG8_STAGE(PG8_SA(0, 0), cA, voffA); PG8_STAGE(PG8_SA(0, 1), cA + hstepA, voffA);
;     if (wr == 1) PG8_BAR;
;     PG8_WAIT_V(2); PG8_BAR;
;     PG8_STAGE(PG8_SB(1, 0), cB + kstep, voffB); PG8_STAGE(PG8_SA(1, 0), cA + kstep, voffA); PG8_STAGE(PG8_SB(1, 1), cB + hstepB + kstep, voffB);
;     PG8_WAIT_V(6); PG8_BAR;
.LBB0_427:
	s_and_b32 s8, s4, 3
	s_lshl_b32 s59, s1, 6
	s_lshl_b32 s1, s1, 13
	s_lshl_b32 s60, s8, 5
	s_lshl_b32 s9, s8, 12
	v_readlane_b32 s4, v254, 28
	v_readlane_b32 s12, v254, 49
	v_readlane_b32 s5, v254, 29
	s_add_u32 s4, s12, s4
	v_readlane_b32 s12, v254, 50
	s_addc_u32 s5, s12, s5
	v_readlane_b32 s12, v254, 40
	v_readlane_b32 s13, v254, 41
	s_add_u32 s26, s4, s12
	s_addc_u32 s27, s5, s13
	s_cmp_eq_u64 s[4:5], 0
	s_cselect_b64 s[28:29], -1, 0
	s_cmp_lg_u64 s[4:5], 0
	s_cselect_b64 s[30:31], -1, 0
	s_cmp_eq_u64 s[26:27], 0
	s_cselect_b64 s[34:35], -1, 0
	s_add_i32 m0, s55, 0x18000
	v_lshl_add_u64 v[8:9], v[8:9], 0, s[2:3]
	global_load_lds_dwordx4 v[8:9], off
	v_lshl_add_u64 v[6:7], v[6:7], 0, s[2:3]
	s_add_i32 m0, s55, 0x1a000
	s_add_i32 s61, s55, 0x8000
	s_add_i32 s62, s55, 0xa000
	global_load_lds_dwordx4 v[6:7], off
	v_lshl_add_u64 v[2:3], v[2:3], 0, s[2:3]
	s_mov_b32 m0, s61
	s_add_u32 s4, s10, 0x40080
	global_load_lds_dwordx4 v[2:3], off
	v_lshl_add_u64 v[2:3], v[4:5], 0, s[2:3]
	s_mov_b32 m0, s62
	s_addc_u32 s5, s11, 0
	global_load_lds_dwordx4 v[2:3], off
	s_add_i32 m0, s55, 0x1c000
	v_lshl_add_u64 v[2:3], s[4:5], 0, v[0:1]
	global_load_lds_dwordx4 v[2:3], off
	v_lshl_add_u64 v[2:3], s[4:5], 0, v[130:131]
	s_add_i32 m0, s55, 0x1e000
	s_movk_i32 s4, 0x3c0
	global_load_lds_dwordx4 v[2:3], off
	s_waitcnt vmcnt(8)
	s_barrier
	v_and_b32_e32 v2, 48, v10
	v_lshlrev_b32_e32 v3, 6, v10
	v_and_or_b32 v2, v3, s4, v2
	v_lshlrev_b32_e32 v3, 2, v10
	v_and_b32_e32 v3, 32, v3
	v_bitop3_b32 v4, v2, s1, v3 bitop3:0xde
	v_bitop3_b32 v148, v2, s9, v3 bitop3:0xde
	v_lshlrev_b32_e32 v2, 14, v15
	v_and_b32_e32 v2, 0xffff8000, v2
	v_lshl_add_u32 v2, v14, 11, v2
	v_and_b32_e32 v3, 1, v15
	v_lshl_or_b32 v2, v3, 6, v2
	v_lshl_add_u32 v136, v16, 1, v2
	v_lshlrev_b32_e32 v2, 14, v11
	v_and_b32_e32 v2, 0xffff8000, v2
	s_waitcnt vmcnt(6)
	s_cmpk_lt_u32 s0, 0x100
	v_lshl_add_u32 v2, v12, 11, v2
	v_and_b32_e32 v3, 1, v11
	s_cselect_b64 s[36:37], -1, 0
	s_cmp_eq_u32 s8, 0
	v_lshl_or_b32 v2, v3, 6, v2
	v_readlane_b32 s4, v253, 45
	s_mov_b32 s63, 0
	s_cselect_b64 s[38:39], -1, 0
	v_mov_b32_e32 v137, v1
	v_lshl_add_u32 v138, v13, 1, v2
	v_mov_b32_e32 v139, v1
	v_add_u32_e32 v149, 0x100, v4
	v_readlane_b32 s0, v253, 29
	s_mov_b32 s1, s4
	s_barrier
	v_readlane_b32 s5, v253, 46
	s_branch .LBB0_430

; #define PG8_STAGE(bufoff, gbase, voff) do { _Pragma("unroll") for (int _i = 0; _i < 2; ++_i) \
;         __builtin_amdgcn_global_load_lds((const unsigned*)((const char*)(gbase) + (voff)[_i]), (LAS unsigned*)(lds + (bufoff) + ldsw + _i * 8192), 16, 0, 0); } while (0)
; #define PG8_WAIT_V(n) asm volatile("s_waitcnt vmcnt(" #n ")" ::: "memory")
; #define PG8_BAR __builtin_amdgcn_s_barrier()
; template <class Epi, bool HALFM = false>
; DI void gemm_phase(LAS unsigned char* lds, const Gemm g, const StaticOrder& S, const Epi& E) {
;     ...
;     PG8_STAGE(PG8_SB(0, 0), cB, voffB); PG8_STAGE(PG8_SB(0, 1), cB + hstepB, voffB); PG8_STAGE(PG8_SA(0, 0), cA, voffA); PG8_STAGE(PG8_SA(0, 1), cA + hstepA, voffA);
;     if (wr == 1) PG8_BAR;
;     PG8_WAIT_V(2); PG8_BAR;
;     PG8_STAGE(PG8_SB(1, 0), cB + kstep, voffB); PG8_STAGE(PG8_SA(1, 0), cA + kstep, voffA); PG8_STAGE(PG8_SB(1, 1), cB + hstepB + kstep, voffB);
;     PG8_WAIT_V(6); PG8_BAR;
.LBB0_558:
	s_add_i32 m0, s42, 0x18000
	v_lshl_add_u64 v[2:3], v[2:3], 0, s[2:3]
	global_load_lds_dwordx4 v[2:3], off
	v_lshl_add_u64 v[2:3], v[4:5], 0, s[2:3]
	s_add_i32 m0, s42, 0x1a000
	s_add_i32 s46, s42, 0x8000
	global_load_lds_dwordx4 v[2:3], off
	v_lshl_add_u64 v[2:3], v[10:11], 0, s[2:3]
	s_mov_b32 m0, s46
	s_add_i32 s47, s42, 0xa000
	global_load_lds_dwordx4 v[2:3], off
	v_lshl_add_u64 v[2:3], v[12:13], 0, s[2:3]
	s_mov_b32 m0, s47
	s_movk_i32 s8, 0x3c0
	global_load_lds_dwordx4 v[2:3], off
	s_add_i32 m0, s42, 0x1c000
	v_lshl_add_u64 v[2:3], v[6:7], 0, s[2:3]
	global_load_lds_dwordx4 v[2:3], off
	v_lshl_add_u64 v[2:3], v[8:9], 0, s[2:3]
	s_add_i32 m0, s42, 0x1e000
	s_lshl_b32 s6, s6, 5
	global_load_lds_dwordx4 v[2:3], off
	s_waitcnt vmcnt(8)
	s_barrier
	v_and_b32_e32 v2, 48, v14
	v_lshlrev_b32_e32 v3, 6, v14
	v_and_or_b32 v2, v3, s8, v2
	v_lshlrev_b32_e32 v3, 2, v14
	s_and_b32 s50, s6, 0x60
	s_lshl_b32 s49, s7, 6
	s_lshl_b32 s7, s7, 13
	v_and_b32_e32 v3, 32, v3
	s_lshl_b32 s6, s50, 7
	v_bitop3_b32 v4, v2, s7, v3 bitop3:0xde
	v_bitop3_b32 v144, s6, v2, v3 bitop3:0xf6
	v_cvt_f32_ubyte0_e32 v2, s1
	v_rcp_iflag_f32_e32 v2, v2
	s_lshr_b32 s48, s15, 6
	s_add_i32 s51, s48, -2
	s_cmpk_lt_u32 s24, 0x100
	v_mul_f32_e32 v2, 0x4f7ffffe, v2
	v_cvt_u32_f32_e32 v2, v2
	s_cselect_b64 s[24:25], -1, 0
	s_ashr_i32 s52, s40, 31
	s_lshr_b32 s53, s14, 3
	s_cmp_eq_u64 s[16:17], 0
	s_cselect_b64 s[26:27], -1, 0
	s_cmp_lg_u64 s[16:17], 0
	v_readfirstlane_b32 s7, v2
	v_add_u32_e32 v2, v17, v15
	s_cselect_b64 s[28:29], -1, 0
	s_sub_i32 s6, 0, s1
	v_add_lshl_u32 v2, v2, v16, 1
	v_mov_b32_e32 v3, v1
	s_waitcnt vmcnt(6)
	s_mul_i32 s6, s6, s7
	v_lshl_add_u64 v[136:137], s[66:67], 0, v[2:3]
	v_add_u32_e32 v2, v20, v18
	s_mul_hi_u32 s6, s7, s6
	v_add_lshl_u32 v2, v2, v19, 1
	s_mov_b32 s15, s67
	s_mov_b32 s54, 0
	s_add_i32 s55, s7, s6
	v_lshl_add_u64 v[138:139], s[66:67], 0, v[2:3]
	v_add_u32_e32 v145, 0x100, v4
	s_barrier
	s_branch .LBB0_561

; #define PG8_STAGE(bufoff, gbase, voff) do { _Pragma("unroll") for (int _i = 0; _i < 2; ++_i) \
;         __builtin_amdgcn_global_load_lds((const unsigned*)((const char*)(gbase) + (voff)[_i]), (LAS unsigned*)(lds + (bufoff) + ldsw + _i * 8192), 16, 0, 0); } while (0)
; #define PG8_WAIT_V(n) asm volatile("s_waitcnt vmcnt(" #n ")" ::: "memory")
; #define PG8_BAR __builtin_amdgcn_s_barrier()
; template <class Epi, bool HALFM = false>
; DI void gemm_phase(LAS unsigned char* lds, const Gemm g, const StaticOrder& S, const Epi& E) {
;     ...
;     PG8_STAGE(PG8_SB(0, 0), cB, voffB); PG8_STAGE(PG8_SB(0, 1), cB + hstepB, voffB); PG8_STAGE(PG8_SA(0, 0), cA, voffA); PG8_STAGE(PG8_SA(0, 1), cA + hstepA, voffA);
;     if (wr == 1) PG8_BAR;
;     PG8_WAIT_V(2); PG8_BAR;
;     PG8_STAGE(PG8_SB(1, 0), cB + kstep, voffB); PG8_STAGE(PG8_SA(1, 0), cA + kstep, voffA); PG8_STAGE(PG8_SB(1, 1), cB + hstepB + kstep, voffB);
;     PG8_WAIT_V(6); PG8_BAR;
.LBB0_599:
	v_readlane_b32 s8, v254, 34
	v_readlane_b32 s5, v254, 49
	v_readlane_b32 s9, v254, 35
	s_add_u32 s5, s5, s8
	v_readlane_b32 s8, v254, 50
	s_addc_u32 s10, s8, s9
	v_readlane_b32 s8, v254, 13
	v_readlane_b32 s12, v254, 61
	v_readlane_b32 s13, v254, 62
	s_add_u32 s12, s12, s8
	v_readlane_b32 s8, v254, 36
	s_addc_u32 s11, s13, 0
	v_readlane_b32 s9, v254, 37
	s_and_b64 s[8:9], s[8:9], exec
	s_cselect_b32 s11, s10, s11
	s_cselect_b32 s10, s5, s12
	s_lshl_b32 s1, s1, 5
	s_and_b32 s40, s1, 0x60
	s_add_i32 m0, s35, 0x18000
	v_lshl_add_u64 v[8:9], v[8:9], 0, s[2:3]
	s_lshl_b32 s39, s4, 6
	s_lshl_b32 s8, s4, 13
	s_lshl_b32 s1, s40, 7
	global_load_lds_dwordx4 v[8:9], off
	v_lshl_add_u64 v[6:7], v[6:7], 0, s[2:3]
	s_add_i32 m0, s35, 0x1a000
	s_add_i32 s41, s35, 0x8000
	s_add_i32 s42, s35, 0xa000
	global_load_lds_dwordx4 v[6:7], off
	v_lshl_add_u64 v[2:3], v[2:3], 0, s[2:3]
	s_mov_b32 m0, s41
	s_add_u32 s4, s26, 0x40080
	global_load_lds_dwordx4 v[2:3], off
	v_lshl_add_u64 v[2:3], v[4:5], 0, s[2:3]
	s_mov_b32 m0, s42
	s_addc_u32 s5, s27, 0
	global_load_lds_dwordx4 v[2:3], off
	s_add_i32 m0, s35, 0x1c000
	v_lshl_add_u64 v[2:3], s[4:5], 0, v[0:1]
	global_load_lds_dwordx4 v[2:3], off
	v_lshl_add_u64 v[2:3], s[4:5], 0, v[130:131]
	s_add_i32 m0, s35, 0x1e000
	s_movk_i32 s4, 0x3c0
	global_load_lds_dwordx4 v[2:3], off
	s_waitcnt vmcnt(8)
	s_barrier
	v_and_b32_e32 v2, 48, v10
	v_lshlrev_b32_e32 v3, 6, v10
	v_and_or_b32 v2, v3, s4, v2
	v_lshlrev_b32_e32 v3, 2, v10
	v_and_b32_e32 v3, 32, v3
	v_bitop3_b32 v4, v2, s8, v3 bitop3:0xde
	v_bitop3_b32 v144, s1, v2, v3 bitop3:0xf6
	v_lshlrev_b32_e32 v2, 14, v15
	v_and_b32_e32 v2, 0xffff8000, v2
	v_lshl_add_u32 v2, v14, 11, v2
	v_and_b32_e32 v3, 1, v15
	v_lshl_or_b32 v2, v3, 6, v2
	v_lshl_add_u32 v136, v16, 1, v2
	v_lshlrev_b32_e32 v2, 14, v11
	v_and_b32_e32 v2, 0xffff8000, v2
	s_waitcnt vmcnt(6)
	v_lshl_add_u32 v2, v12, 11, v2
	v_and_b32_e32 v3, 1, v11
	s_cmpk_lt_u32 s0, 0x100
	v_lshl_or_b32 v2, v3, 6, v2
	v_readlane_b32 s4, v253, 31
	s_cselect_b64 s[12:13], -1, 0
	v_mov_b32_e32 v137, v1
	v_lshl_add_u32 v138, v13, 1, v2
	v_mov_b32_e32 v139, v1
	s_mov_b32 s43, 0
	v_add_u32_e32 v145, 0x100, v4
	v_readlane_b32 s0, v253, 30
	s_mov_b32 s1, s4
	s_barrier
	v_readlane_b32 s5, v253, 32
	s_branch .LBB0_602
